# gate-up epilogue: early wave half takes its re-alignment barrier after its first row-group store (about one quarter of the epilogue) instead of before the epilogue
# baseline (speedup 1.0000x reference)
; __device__ __forceinline__ float silu_f(float g) { return g * __builtin_amdgcn_rcpf(1.0f + __builtin_amdgcn_exp2f(g * -1.4426950408889634f)); }
; __device__ __forceinline__ void rstd8(const float* ss, int row0, float (&rs)[2][4]) {
;     f32x4 p[2][4];
; #pragma unroll
;     for (int ai = 0; ai < 2; ++ai)
; #pragma unroll
;         for (int m = 0; m < 4; ++m) p[ai][m] = *(const f32x4*)(ss + 4 * (size_t)(row0 + ai * HALF + m * 16));
; #pragma unroll
;     for (int ai = 0; ai < 2; ++ai)
; #pragma unroll
;         for (int m = 0; m < 4; ++m) rs[ai][m] = __builtin_amdgcn_rsqf(((p[ai][m].x + p[ai][m].y) + (p[ai][m].z + p[ai][m].w)) * (1.0f / D) + EPS);
;     __device__ __forceinline__ void operator()(const f32x4 (&acc)[2][2][4][2], const Unit& u, int wr, int wc, int fr, int fq) const {
;     ...
;         float rsv[2][4]; rstd8(ss, row0, rsv);
; #pragma unroll
;         for (int ai = 0; ai < 2; ++ai)
; #pragma unroll
;             for (int m = 0; m < 4; ++m) { const int row = row0 + ai * HALF + m * 16; const float rs = rsv[ai][m];
;                 f32x4 g0 = acc[ai][0][m][0] * rs, g1 = acc[ai][0][m][1] * rs; const f32x4 t0 = acc[ai][1][m][0] * rs, t1 = acc[ai][1][m][1] * rs;
;                 if (silu) {
; #pragma unroll
;                     for (int j = 0; j < 4; ++j) { g0[j] = silu_f(g0[j]); g1[j] = silu_f(g1[j]); } }
.LBB0_309:
	s_lshl_b32 s4, s54, 8
	s_add_i32 s4, s4, s89
	v_or_b32_e32 v172, s4, v183
	v_ashrrev_i32_e32 v173, 31, v172
	v_or_b32_e32 v170, 16, v172
	v_lshl_add_u64 v[74:75], v[172:173], 4, s[24:25]
	v_ashrrev_i32_e32 v171, 31, v170
	v_lshl_add_u64 v[76:77], v[170:171], 4, s[24:25]
	global_load_dwordx4 v[174:177], v[74:75], off
	global_load_dwordx4 v[154:157], v[76:77], off
	v_or_b32_e32 v168, 32, v172
	v_or_b32_e32 v166, 48, v172
	v_ashrrev_i32_e32 v169, 31, v168
	v_ashrrev_i32_e32 v167, 31, v166
	v_add_u32_e32 v164, 0x80, v172
	v_add_u32_e32 v162, 0x90, v172
	v_lshl_add_u64 v[74:75], v[168:169], 4, s[24:25]
	v_lshl_add_u64 v[76:77], v[166:167], 4, s[24:25]
	v_ashrrev_i32_e32 v165, 31, v164
	v_ashrrev_i32_e32 v163, 31, v162
	v_add_u32_e32 v160, 0xa0, v172
	v_add_u32_e32 v158, 0xb0, v172
	global_load_dwordx4 v[150:153], v[74:75], off
	global_load_dwordx4 v[146:149], v[76:77], off
	v_lshl_add_u64 v[74:75], v[164:165], 4, s[24:25]
	v_lshl_add_u64 v[76:77], v[162:163], 4, s[24:25]
	v_ashrrev_i32_e32 v161, 31, v160
	v_ashrrev_i32_e32 v159, 31, v158
	global_load_dwordx4 v[134:137], v[74:75], off
	global_load_dwordx4 v[114:117], v[76:77], off
	v_lshl_add_u64 v[74:75], v[160:161], 4, s[24:25]
	v_lshl_add_u64 v[76:77], v[158:159], 4, s[24:25]
	global_load_dwordx4 v[94:97], v[74:75], off
	s_nop 0
	global_load_dwordx4 v[74:77], v[76:77], off
	s_and_b64 vcc, exec, s[6:7]
	s_waitcnt vmcnt(0) lgkmcnt(0)
	v_mov_b32_e32 v178, v175
	v_mov_b32_e32 v179, v176
	v_mov_b32_e32 v175, v177
	v_pk_add_f32 v[174:175], v[178:179], v[174:175]
	s_nop 0
	v_add_f32_e32 v159, v174, v175
	v_fmamk_f32 v159, v159, 0x3a800000, v224
	v_rsq_f32_e32 v174, v159
	s_nop 0
	v_pk_mul_f32 v[176:177], v[144:145], v[174:175] op_sel_hi:[1,0]
	v_pk_mul_f32 v[178:179], v[142:143], v[174:175] op_sel_hi:[1,0]
	v_pk_mul_f32 v[142:143], v[140:141], v[174:175] op_sel_hi:[1,0]
	v_pk_mul_f32 v[144:145], v[138:139], v[174:175] op_sel_hi:[1,0]
	s_cbranch_vccnz .LBB0_311
	v_mul_f32_e32 v139, 0xbfb8aa3b, v144
	v_exp_f32_e32 v139, v139
	v_mul_f32_e32 v159, 0xbfb8aa3b, v176
	v_exp_f32_e32 v159, v159
	v_mul_f32_e32 v138, 0xbfb8aa3b, v178
	v_add_f32_e32 v139, 1.0, v139
	v_rcp_f32_e32 v140, v139
	v_mul_f32_e32 v139, 0xbfb8aa3b, v179
	v_exp_f32_e32 v138, v138
	v_exp_f32_e32 v139, v139
	v_add_f32_e32 v159, 1.0, v159
	v_rcp_f32_e32 v188, v159
	v_mul_f32_e32 v159, 0xbfb8aa3b, v142
	v_add_f32_e32 v138, 1.0, v138
	v_add_f32_e32 v139, 1.0, v139
	v_exp_f32_e32 v159, v159
	v_rcp_f32_e32 v138, v138
	v_rcp_f32_e32 v139, v139
	v_mul_f32_e32 v141, 0xbfb8aa3b, v145
	v_add_f32_e32 v159, 1.0, v159
	v_rcp_f32_e32 v190, v159
	v_mul_f32_e32 v159, 0xbfb8aa3b, v177
	v_pk_mul_f32 v[178:179], v[178:179], v[138:139]
	v_mul_f32_e32 v138, 0xbfb8aa3b, v143
	v_exp_f32_e32 v141, v141
	v_exp_f32_e32 v159, v159
	v_exp_f32_e32 v138, v138
	v_add_f32_e32 v141, 1.0, v141
	v_add_f32_e32 v159, 1.0, v159
	v_add_f32_e32 v138, 1.0, v138
	v_rcp_f32_e32 v141, v141
	v_rcp_f32_e32 v189, v159
	v_rcp_f32_e32 v191, v138
	v_pk_mul_f32 v[144:145], v[144:145], v[140:141]
	v_pk_mul_f32 v[176:177], v[176:177], v[188:189]
	v_pk_mul_f32 v[142:143], v[142:143], v[190:191]

; __device__ __forceinline__ unsigned cvt_pk_bf16(float lo, float hi) { unsigned r; asm volatile("v_cvt_pk_bf16_f32 %0, %1, %2" : "=v"(r) : "v"(lo), "v"(hi)); return r; }
; __device__ __forceinline__ float silu_f(float g) { return g * __builtin_amdgcn_rcpf(1.0f + __builtin_amdgcn_exp2f(g * -1.4426950408889634f)); }
;     __device__ __forceinline__ void operator()(const f32x4 (&acc)[2][2][4][2], const Unit& u, int wr, int wc, int fr, int fq) const {
;     ...
;             for (int m = 0; m < 4; ++m) { const int row = row0 + ai * HALF + m * 16; const float rs = rsv[ai][m];
;                 f32x4 g0 = acc[ai][0][m][0] * rs, g1 = acc[ai][0][m][1] * rs; const f32x4 t0 = acc[ai][1][m][0] * rs, t1 = acc[ai][1][m][1] * rs;
;                 if (silu) {
; #pragma unroll
;                     for (int j = 0; j < 4; ++j) { g0[j] = silu_f(g0[j]); g1[j] = silu_f(g1[j]); } }
;                 g0 = g0 * t0; g1 = g1 * t1;
;                 u32x4 w; w.x = cvt_pk_bf16(g0[0], g0[1]); w.y = cvt_pk_bf16(g0[2], g0[3]); w.z = cvt_pk_bf16(g1[0], g1[1]); w.w = cvt_pk_bf16(g1[2], g1[3]);
;                 *(u32x4*)(O + (size_t)row * ldc + col0 + (size_t)(row >> 12) * adj) = w; }
.Lep_have_rs:
	v_pk_mul_f32 v[146:147], v[142:143], v[240:241] op_sel_hi:[1,0]
	v_pk_mul_f32 v[148:149], v[144:145], v[240:241] op_sel_hi:[1,0]
	v_pk_mul_f32 v[150:151], v[138:139], v[240:241] op_sel_hi:[1,0]
	v_pk_mul_f32 v[152:153], v[140:141], v[240:241] op_sel_hi:[1,0]
	v_exp_f32_e32 v146, v146
	v_exp_f32_e32 v147, v147
	v_exp_f32_e32 v148, v148
	v_exp_f32_e32 v149, v149
	v_exp_f32_e32 v150, v150
	v_exp_f32_e32 v151, v151
	v_exp_f32_e32 v152, v152
	v_exp_f32_e32 v153, v153
	v_pk_mul_f32 v[142:143], v[142:143], v[130:131]
	v_pk_mul_f32 v[144:145], v[144:145], v[132:133]
	v_pk_mul_f32 v[138:139], v[138:139], v[126:127]
	v_pk_mul_f32 v[140:141], v[140:141], v[128:129]
	v_pk_fma_f32 v[146:147], v[146:147], v[240:241], v[240:241] op_sel:[0,1,1] op_sel_hi:[1,1,1]
	v_pk_fma_f32 v[148:149], v[148:149], v[240:241], v[240:241] op_sel:[0,1,1] op_sel_hi:[1,1,1]
	v_pk_fma_f32 v[150:151], v[150:151], v[240:241], v[240:241] op_sel:[0,1,1] op_sel_hi:[1,1,1]
	v_pk_fma_f32 v[152:153], v[152:153], v[240:241], v[240:241] op_sel:[0,1,1] op_sel_hi:[1,1,1]
	v_rcp_f32_e32 v146, v146
	v_rcp_f32_e32 v147, v147
	v_rcp_f32_e32 v148, v148
	v_rcp_f32_e32 v149, v149
	v_rcp_f32_e32 v150, v150
	v_rcp_f32_e32 v151, v151
	v_rcp_f32_e32 v152, v152
	v_rcp_f32_e32 v153, v153
	v_pk_mul_f32 v[154:155], v[122:123], v[242:243] op_sel_hi:[1,0]
	v_pk_mul_f32 v[156:157], v[124:125], v[242:243] op_sel_hi:[1,0]
	v_pk_mul_f32 v[158:159], v[118:119], v[242:243] op_sel_hi:[1,0]
	v_pk_mul_f32 v[160:161], v[120:121], v[242:243] op_sel_hi:[1,0]
	v_pk_mul_f32 v[142:143], v[142:143], v[146:147]
	v_pk_mul_f32 v[144:145], v[144:145], v[148:149]
	v_pk_mul_f32 v[138:139], v[138:139], v[150:151]
	v_pk_mul_f32 v[140:141], v[140:141], v[152:153]
	v_cvt_pk_bf16_f32 v162, v142, v143
	v_cvt_pk_bf16_f32 v163, v144, v145
	v_cvt_pk_bf16_f32 v164, v138, v139
	v_cvt_pk_bf16_f32 v165, v140, v141
	global_store_dwordx4 v190, v[162:165], s[10:11] sc1
	v_readlane_b32 s4, v254, 46
	v_readlane_b32 s5, v254, 47
	s_cmp_lg_u64 s[4:5], 0
	s_cbranch_scc0 .Lep_fast_nobar
	s_barrier
.Lep_fast_nobar:
	v_add_u32_e32 v190, s30, v190
	v_exp_f32_e32 v154, v154
	v_exp_f32_e32 v155, v155
	v_exp_f32_e32 v156, v156
	v_exp_f32_e32 v157, v157
	v_exp_f32_e32 v158, v158
	v_exp_f32_e32 v159, v159
	v_exp_f32_e32 v160, v160
	v_exp_f32_e32 v161, v161
	v_pk_mul_f32 v[122:123], v[122:123], v[110:111]
	v_pk_mul_f32 v[124:125], v[124:125], v[112:113]
	v_pk_mul_f32 v[118:119], v[118:119], v[106:107]
	v_pk_mul_f32 v[120:121], v[120:121], v[108:109]
	v_pk_fma_f32 v[154:155], v[154:155], v[242:243], v[242:243] op_sel:[0,1,1] op_sel_hi:[1,1,1]
	v_pk_fma_f32 v[156:157], v[156:157], v[242:243], v[242:243] op_sel:[0,1,1] op_sel_hi:[1,1,1]
	v_pk_fma_f32 v[158:159], v[158:159], v[242:243], v[242:243] op_sel:[0,1,1] op_sel_hi:[1,1,1]
	v_pk_fma_f32 v[160:161], v[160:161], v[242:243], v[242:243] op_sel:[0,1,1] op_sel_hi:[1,1,1]
	v_rcp_f32_e32 v154, v154
	v_rcp_f32_e32 v155, v155
	v_rcp_f32_e32 v156, v156
	v_rcp_f32_e32 v157, v157
	v_rcp_f32_e32 v158, v158
	v_rcp_f32_e32 v159, v159
	v_rcp_f32_e32 v160, v160
	v_rcp_f32_e32 v161, v161
	v_pk_mul_f32 v[146:147], v[102:103], v[244:245] op_sel_hi:[1,0]
	v_pk_mul_f32 v[148:149], v[104:105], v[244:245] op_sel_hi:[1,0]
	v_pk_mul_f32 v[150:151], v[98:99], v[244:245] op_sel_hi:[1,0]
	v_pk_mul_f32 v[152:153], v[100:101], v[244:245] op_sel_hi:[1,0]
	v_pk_mul_f32 v[122:123], v[122:123], v[154:155]
	v_pk_mul_f32 v[124:125], v[124:125], v[156:157]
	v_pk_mul_f32 v[118:119], v[118:119], v[158:159]
	v_pk_mul_f32 v[120:121], v[120:121], v[160:161]
	v_cvt_pk_bf16_f32 v166, v122, v123
	v_cvt_pk_bf16_f32 v167, v124, v125
	v_cvt_pk_bf16_f32 v168, v118, v119
	v_cvt_pk_bf16_f32 v169, v120, v121
	global_store_dwordx4 v190, v[166:169], s[10:11] sc1
	v_add_u32_e32 v190, s30, v190
	v_exp_f32_e32 v146, v146
	v_exp_f32_e32 v147, v147
	v_exp_f32_e32 v148, v148
	v_exp_f32_e32 v149, v149
	v_exp_f32_e32 v150, v150
	v_exp_f32_e32 v151, v151
	v_exp_f32_e32 v152, v152
	v_exp_f32_e32 v153, v153
	v_pk_mul_f32 v[102:103], v[102:103], v[90:91]
	v_pk_mul_f32 v[104:105], v[104:105], v[92:93]
	v_pk_mul_f32 v[98:99], v[98:99], v[86:87]
	v_pk_mul_f32 v[100:101], v[100:101], v[88:89]
	v_pk_fma_f32 v[146:147], v[146:147], v[244:245], v[244:245] op_sel:[0,1,1] op_sel_hi:[1,1,1]
	v_pk_fma_f32 v[148:149], v[148:149], v[244:245], v[244:245] op_sel:[0,1,1] op_sel_hi:[1,1,1]
	v_pk_fma_f32 v[150:151], v[150:151], v[244:245], v[244:245] op_sel:[0,1,1] op_sel_hi:[1,1,1]
	v_pk_fma_f32 v[152:153], v[152:153], v[244:245], v[244:245] op_sel:[0,1,1] op_sel_hi:[1,1,1]
	v_rcp_f32_e32 v146, v146
	v_rcp_f32_e32 v147, v147
	v_rcp_f32_e32 v148, v148
	v_rcp_f32_e32 v149, v149
	v_rcp_f32_e32 v150, v150
	v_rcp_f32_e32 v151, v151
	v_rcp_f32_e32 v152, v152
	v_rcp_f32_e32 v153, v153
	v_pk_mul_f32 v[154:155], v[82:83], v[246:247] op_sel_hi:[1,0]
	v_pk_mul_f32 v[156:157], v[84:85], v[246:247] op_sel_hi:[1,0]
	v_pk_mul_f32 v[158:159], v[78:79], v[246:247] op_sel_hi:[1,0]
	v_pk_mul_f32 v[160:161], v[80:81], v[246:247] op_sel_hi:[1,0]
	v_pk_mul_f32 v[102:103], v[102:103], v[146:147]
	v_pk_mul_f32 v[104:105], v[104:105], v[148:149]
	v_pk_mul_f32 v[98:99], v[98:99], v[150:151]
	v_pk_mul_f32 v[100:101], v[100:101], v[152:153]
	v_cvt_pk_bf16_f32 v162, v102, v103
	v_cvt_pk_bf16_f32 v163, v104, v105
	v_cvt_pk_bf16_f32 v164, v98, v99
	v_cvt_pk_bf16_f32 v165, v100, v101
	global_store_dwordx4 v190, v[162:165], s[10:11] sc1
	v_add_u32_e32 v190, s30, v190
	v_exp_f32_e32 v154, v154
	v_exp_f32_e32 v155, v155
	v_exp_f32_e32 v156, v156
	v_exp_f32_e32 v157, v157
	v_exp_f32_e32 v158, v158
	v_exp_f32_e32 v159, v159
	v_exp_f32_e32 v160, v160
	v_exp_f32_e32 v161, v161
	v_pk_mul_f32 v[82:83], v[82:83], v[70:71]
; __device__ __forceinline__ unsigned cvt_pk_bf16(float lo, float hi) { unsigned r; asm volatile("v_cvt_pk_bf16_f32 %0, %1, %2" : "=v"(r) : "v"(lo), "v"(hi)); return r; }
; __device__ __forceinline__ float silu_f(float g) { return g * __builtin_amdgcn_rcpf(1.0f + __builtin_amdgcn_exp2f(g * -1.4426950408889634f)); }
;     __device__ __forceinline__ void operator()(const f32x4 (&acc)[2][2][4][2], const Unit& u, int wr, int wc, int fr, int fq) const {
;     ...
;             for (int m = 0; m < 4; ++m) { const int row = row0 + ai * HALF + m * 16; const float rs = rsv[ai][m];
;                 f32x4 g0 = acc[ai][0][m][0] * rs, g1 = acc[ai][0][m][1] * rs; const f32x4 t0 = acc[ai][1][m][0] * rs, t1 = acc[ai][1][m][1] * rs;
;                 if (silu) {
; #pragma unroll
;                     for (int j = 0; j < 4; ++j) { g0[j] = silu_f(g0[j]); g1[j] = silu_f(g1[j]); } }
;                 g0 = g0 * t0; g1 = g1 * t1;
;                 u32x4 w; w.x = cvt_pk_bf16(g0[0], g0[1]); w.y = cvt_pk_bf16(g0[2], g0[3]); w.z = cvt_pk_bf16(g1[0], g1[1]); w.w = cvt_pk_bf16(g1[2], g1[3]);
;                 *(u32x4*)(O + (size_t)row * ldc + col0 + (size_t)(row >> 12) * adj) = w; }
	v_pk_mul_f32 v[84:85], v[84:85], v[72:73]
	v_pk_mul_f32 v[78:79], v[78:79], v[66:67]
	v_pk_mul_f32 v[80:81], v[80:81], v[68:69]
	v_pk_fma_f32 v[154:155], v[154:155], v[246:247], v[246:247] op_sel:[0,1,1] op_sel_hi:[1,1,1]
	v_pk_fma_f32 v[156:157], v[156:157], v[246:247], v[246:247] op_sel:[0,1,1] op_sel_hi:[1,1,1]
	v_pk_fma_f32 v[158:159], v[158:159], v[246:247], v[246:247] op_sel:[0,1,1] op_sel_hi:[1,1,1]
	v_pk_fma_f32 v[160:161], v[160:161], v[246:247], v[246:247] op_sel:[0,1,1] op_sel_hi:[1,1,1]
	v_rcp_f32_e32 v154, v154
	v_rcp_f32_e32 v155, v155
	v_rcp_f32_e32 v156, v156
	v_rcp_f32_e32 v157, v157
	v_rcp_f32_e32 v158, v158
	v_rcp_f32_e32 v159, v159
	v_rcp_f32_e32 v160, v160
	v_rcp_f32_e32 v161, v161
	v_pk_mul_f32 v[146:147], v[62:63], v[248:249] op_sel_hi:[1,0]
	v_pk_mul_f32 v[148:149], v[64:65], v[248:249] op_sel_hi:[1,0]
	v_pk_mul_f32 v[150:151], v[58:59], v[248:249] op_sel_hi:[1,0]
	v_pk_mul_f32 v[152:153], v[60:61], v[248:249] op_sel_hi:[1,0]
	v_pk_mul_f32 v[82:83], v[82:83], v[154:155]
	v_pk_mul_f32 v[84:85], v[84:85], v[156:157]
	v_pk_mul_f32 v[78:79], v[78:79], v[158:159]
	v_pk_mul_f32 v[80:81], v[80:81], v[160:161]
	v_cvt_pk_bf16_f32 v166, v82, v83
	v_cvt_pk_bf16_f32 v167, v84, v85
	v_cvt_pk_bf16_f32 v168, v78, v79
	v_cvt_pk_bf16_f32 v169, v80, v81
	global_store_dwordx4 v190, v[166:169], s[10:11] sc1
	v_add_u32_e32 v190, s31, v190
	v_exp_f32_e32 v146, v146
	v_exp_f32_e32 v147, v147
	v_exp_f32_e32 v148, v148
	v_exp_f32_e32 v149, v149
	v_exp_f32_e32 v150, v150
	v_exp_f32_e32 v151, v151
	v_exp_f32_e32 v152, v152
	v_exp_f32_e32 v153, v153
	v_pk_mul_f32 v[62:63], v[62:63], v[54:55]
	v_pk_mul_f32 v[64:65], v[64:65], v[56:57]
	v_pk_mul_f32 v[58:59], v[58:59], v[50:51]
	v_pk_mul_f32 v[60:61], v[60:61], v[52:53]
	v_pk_fma_f32 v[146:147], v[146:147], v[248:249], v[248:249] op_sel:[0,1,1] op_sel_hi:[1,1,1]
	v_pk_fma_f32 v[148:149], v[148:149], v[248:249], v[248:249] op_sel:[0,1,1] op_sel_hi:[1,1,1]
	v_pk_fma_f32 v[150:151], v[150:151], v[248:249], v[248:249] op_sel:[0,1,1] op_sel_hi:[1,1,1]
	v_pk_fma_f32 v[152:153], v[152:153], v[248:249], v[248:249] op_sel:[0,1,1] op_sel_hi:[1,1,1]
	v_rcp_f32_e32 v146, v146
	v_rcp_f32_e32 v147, v147
	v_rcp_f32_e32 v148, v148
	v_rcp_f32_e32 v149, v149
	v_rcp_f32_e32 v150, v150
	v_rcp_f32_e32 v151, v151
	v_rcp_f32_e32 v152, v152
	v_rcp_f32_e32 v153, v153
	v_pk_mul_f32 v[154:155], v[46:47], v[250:251] op_sel_hi:[1,0]
	v_pk_mul_f32 v[156:157], v[48:49], v[250:251] op_sel_hi:[1,0]
	v_pk_mul_f32 v[158:159], v[42:43], v[250:251] op_sel_hi:[1,0]
	v_pk_mul_f32 v[160:161], v[44:45], v[250:251] op_sel_hi:[1,0]
	v_pk_mul_f32 v[62:63], v[62:63], v[146:147]
	v_pk_mul_f32 v[64:65], v[64:65], v[148:149]
	v_pk_mul_f32 v[58:59], v[58:59], v[150:151]
	v_pk_mul_f32 v[60:61], v[60:61], v[152:153]
	v_cvt_pk_bf16_f32 v162, v62, v63
	v_cvt_pk_bf16_f32 v163, v64, v65
	v_cvt_pk_bf16_f32 v164, v58, v59
	v_cvt_pk_bf16_f32 v165, v60, v61
	global_store_dwordx4 v190, v[162:165], s[10:11] sc1
	v_add_u32_e32 v190, s30, v190
	v_exp_f32_e32 v154, v154
	v_exp_f32_e32 v155, v155
	v_exp_f32_e32 v156, v156
	v_exp_f32_e32 v157, v157
	v_exp_f32_e32 v158, v158
	v_exp_f32_e32 v159, v159
	v_exp_f32_e32 v160, v160
	v_exp_f32_e32 v161, v161
	v_pk_mul_f32 v[46:47], v[46:47], v[38:39]
	v_pk_mul_f32 v[48:49], v[48:49], v[40:41]
	v_pk_mul_f32 v[42:43], v[42:43], v[34:35]
	v_pk_mul_f32 v[44:45], v[44:45], v[36:37]
	v_pk_fma_f32 v[154:155], v[154:155], v[250:251], v[250:251] op_sel:[0,1,1] op_sel_hi:[1,1,1]
	v_pk_fma_f32 v[156:157], v[156:157], v[250:251], v[250:251] op_sel:[0,1,1] op_sel_hi:[1,1,1]
	v_pk_fma_f32 v[158:159], v[158:159], v[250:251], v[250:251] op_sel:[0,1,1] op_sel_hi:[1,1,1]
	v_pk_fma_f32 v[160:161], v[160:161], v[250:251], v[250:251] op_sel:[0,1,1] op_sel_hi:[1,1,1]
	v_rcp_f32_e32 v154, v154
	v_rcp_f32_e32 v155, v155
	v_rcp_f32_e32 v156, v156
; __device__ __forceinline__ unsigned cvt_pk_bf16(float lo, float hi) { unsigned r; asm volatile("v_cvt_pk_bf16_f32 %0, %1, %2" : "=v"(r) : "v"(lo), "v"(hi)); return r; }
; __device__ __forceinline__ float silu_f(float g) { return g * __builtin_amdgcn_rcpf(1.0f + __builtin_amdgcn_exp2f(g * -1.4426950408889634f)); }
;     __device__ __forceinline__ void operator()(const f32x4 (&acc)[2][2][4][2], const Unit& u, int wr, int wc, int fr, int fq) const {
;     ...
;             for (int m = 0; m < 4; ++m) { const int row = row0 + ai * HALF + m * 16; const float rs = rsv[ai][m];
;                 f32x4 g0 = acc[ai][0][m][0] * rs, g1 = acc[ai][0][m][1] * rs; const f32x4 t0 = acc[ai][1][m][0] * rs, t1 = acc[ai][1][m][1] * rs;
;                 if (silu) {
; #pragma unroll
;                     for (int j = 0; j < 4; ++j) { g0[j] = silu_f(g0[j]); g1[j] = silu_f(g1[j]); } }
;                 g0 = g0 * t0; g1 = g1 * t1;
;                 u32x4 w; w.x = cvt_pk_bf16(g0[0], g0[1]); w.y = cvt_pk_bf16(g0[2], g0[3]); w.z = cvt_pk_bf16(g1[0], g1[1]); w.w = cvt_pk_bf16(g1[2], g1[3]);
;                 *(u32x4*)(O + (size_t)row * ldc + col0 + (size_t)(row >> 12) * adj) = w; }
	v_rcp_f32_e32 v157, v157
	v_rcp_f32_e32 v158, v158
	v_rcp_f32_e32 v159, v159
	v_rcp_f32_e32 v160, v160
	v_rcp_f32_e32 v161, v161
	v_pk_mul_f32 v[146:147], v[30:31], v[252:253] op_sel_hi:[1,0]
	v_pk_mul_f32 v[148:149], v[32:33], v[252:253] op_sel_hi:[1,0]
	v_pk_mul_f32 v[150:151], v[26:27], v[252:253] op_sel_hi:[1,0]
	v_pk_mul_f32 v[152:153], v[28:29], v[252:253] op_sel_hi:[1,0]
	v_pk_mul_f32 v[46:47], v[46:47], v[154:155]
	v_pk_mul_f32 v[48:49], v[48:49], v[156:157]
	v_pk_mul_f32 v[42:43], v[42:43], v[158:159]
	v_pk_mul_f32 v[44:45], v[44:45], v[160:161]
	v_cvt_pk_bf16_f32 v166, v46, v47
	v_cvt_pk_bf16_f32 v167, v48, v49
	v_cvt_pk_bf16_f32 v168, v42, v43
	v_cvt_pk_bf16_f32 v169, v44, v45
	global_store_dwordx4 v190, v[166:169], s[10:11] sc1
	v_add_u32_e32 v190, s30, v190
	v_exp_f32_e32 v146, v146
	v_exp_f32_e32 v147, v147
	v_exp_f32_e32 v148, v148
	v_exp_f32_e32 v149, v149
	v_exp_f32_e32 v150, v150
	v_exp_f32_e32 v151, v151
	v_exp_f32_e32 v152, v152
	v_exp_f32_e32 v153, v153
	v_pk_mul_f32 v[30:31], v[30:31], v[22:23]
	v_pk_mul_f32 v[32:33], v[32:33], v[24:25]
	v_pk_mul_f32 v[26:27], v[26:27], v[18:19]
	v_pk_mul_f32 v[28:29], v[28:29], v[20:21]
	v_pk_fma_f32 v[146:147], v[146:147], v[252:253], v[252:253] op_sel:[0,1,1] op_sel_hi:[1,1,1]
	v_pk_fma_f32 v[148:149], v[148:149], v[252:253], v[252:253] op_sel:[0,1,1] op_sel_hi:[1,1,1]
	v_pk_fma_f32 v[150:151], v[150:151], v[252:253], v[252:253] op_sel:[0,1,1] op_sel_hi:[1,1,1]
	v_pk_fma_f32 v[152:153], v[152:153], v[252:253], v[252:253] op_sel:[0,1,1] op_sel_hi:[1,1,1]
	v_rcp_f32_e32 v146, v146
	v_rcp_f32_e32 v147, v147
	v_rcp_f32_e32 v148, v148
	v_rcp_f32_e32 v149, v149
	v_rcp_f32_e32 v150, v150
	v_rcp_f32_e32 v151, v151
	v_rcp_f32_e32 v152, v152
	v_rcp_f32_e32 v153, v153
	v_pk_mul_f32 v[154:155], v[14:15], v[214:215] op_sel_hi:[1,0]
	v_pk_mul_f32 v[156:157], v[16:17], v[214:215] op_sel_hi:[1,0]
	v_pk_mul_f32 v[158:159], v[10:11], v[214:215] op_sel_hi:[1,0]
	v_pk_mul_f32 v[160:161], v[12:13], v[214:215] op_sel_hi:[1,0]
	v_pk_mul_f32 v[30:31], v[30:31], v[146:147]
	v_pk_mul_f32 v[32:33], v[32:33], v[148:149]
	v_pk_mul_f32 v[26:27], v[26:27], v[150:151]
	v_pk_mul_f32 v[28:29], v[28:29], v[152:153]
	v_cvt_pk_bf16_f32 v162, v30, v31
	v_cvt_pk_bf16_f32 v163, v32, v33
	v_cvt_pk_bf16_f32 v164, v26, v27
	v_cvt_pk_bf16_f32 v165, v28, v29
	global_store_dwordx4 v190, v[162:165], s[10:11] sc1
	v_add_u32_e32 v190, s30, v190
	v_exp_f32_e32 v154, v154
	v_exp_f32_e32 v155, v155
	v_exp_f32_e32 v156, v156
	v_exp_f32_e32 v157, v157
	v_exp_f32_e32 v158, v158
	v_exp_f32_e32 v159, v159
	v_exp_f32_e32 v160, v160
	v_exp_f32_e32 v161, v161
	v_pk_mul_f32 v[14:15], v[14:15], v[6:7]
	v_pk_mul_f32 v[16:17], v[16:17], v[8:9]
	v_pk_mul_f32 v[10:11], v[10:11], v[2:3]
	v_pk_mul_f32 v[12:13], v[12:13], v[4:5]
	v_pk_fma_f32 v[154:155], v[154:155], v[214:215], v[214:215] op_sel:[0,1,1] op_sel_hi:[1,1,1]
	v_pk_fma_f32 v[156:157], v[156:157], v[214:215], v[214:215] op_sel:[0,1,1] op_sel_hi:[1,1,1]
	v_pk_fma_f32 v[158:159], v[158:159], v[214:215], v[214:215] op_sel:[0,1,1] op_sel_hi:[1,1,1]
	v_pk_fma_f32 v[160:161], v[160:161], v[214:215], v[214:215] op_sel:[0,1,1] op_sel_hi:[1,1,1]
	v_rcp_f32_e32 v154, v154
	v_rcp_f32_e32 v155, v155
	v_rcp_f32_e32 v156, v156
	v_rcp_f32_e32 v157, v157
	v_rcp_f32_e32 v158, v158
	v_rcp_f32_e32 v159, v159
	v_rcp_f32_e32 v160, v160
	v_rcp_f32_e32 v161, v161
	v_pk_mul_f32 v[14:15], v[14:15], v[154:155]
	v_pk_mul_f32 v[16:17], v[16:17], v[156:157]
	v_pk_mul_f32 v[10:11], v[10:11], v[158:159]
	v_pk_mul_f32 v[12:13], v[12:13], v[160:161]
	v_cvt_pk_bf16_f32 v166, v14, v15
	v_cvt_pk_bf16_f32 v167, v16, v17
	v_cvt_pk_bf16_f32 v168, v10, v11
	v_cvt_pk_bf16_f32 v169, v12, v13
	global_store_dwordx4 v190, v[166:169], s[10:11] sc1
	s_andn2_b64 vcc, exec, s[8:9]
	s_mov_b64 s[4:5], -1
	s_branch .Lep_join
